# SB loops: K/V fragment LDS addresses formed once per step in spare VGPRs (19 fewer VALU per step); dead s_nop padding keeps the later GEMM loops at their previous byte addresses
# speedup vs baseline: 1.0023x; 1.0023x over previous
; DEV void sb_block(const Params& p, int item) {
;     ...
;   for (int n = 0; n < nsteps; ++n) {
;     const int j = nsteps - 1 - n, buf = n & 3;
;     asm volatile("s_waitcnt vmcnt(8)" ::: "memory");
;     __builtin_amdgcn_s_barrier();
;     asm volatile("" ::: "memory");
;     { const int jn = j > 3 ? j - 3 : 0; SB_DMA(jn, (n + 3) & 3); }
;     const char* lb_ = smem + buf * 32768;
;     int ko0 = KO0, vo0 = VO0;
;     asm volatile("" : "+v"(ko0), "+v"(vo0));
;     if (2 * j + 1 == qt) sb_tile<true>(lb_ + 32 * 256, lb_, ko0, vo0 ^ 64, qf, O, accp, l31, hh);
;     else if (2 * j + 1 < qt) sb_tile<false>(lb_ + 32 * 256, lb_, ko0, vo0 ^ 64, qf, O, accp, l31, hh);
;     if (2 * j == qt) sb_tile<true>(lb_, lb_, ko0, vo0, qf, O, accp, l31, hh);
;     else if (2 * j < qt) sb_tile<false>(lb_, lb_, ko0, vo0, qf, O, accp, l31, hh);
;     asm volatile("" ::: "memory");
;   }
.Lsb_skip_A0:
	v_mov_b64_e32 v[78:79], v[62:63]
	v_mov_b64_e32 v[94:95], v[46:47]
	v_mov_b64_e32 v[110:111], v[30:31]
	v_mov_b64_e32 v[126:127], v[14:15]
	v_mov_b32_e32 v199, v197
	v_mov_b64_e32 v[76:77], v[60:61]
	v_mov_b64_e32 v[74:75], v[58:59]
	v_mov_b64_e32 v[72:73], v[56:57]
	v_mov_b64_e32 v[70:71], v[54:55]
	v_mov_b64_e32 v[68:69], v[52:53]
	v_mov_b64_e32 v[66:67], v[50:51]
	v_mov_b64_e32 v[64:65], v[48:49]
	v_mov_b64_e32 v[92:93], v[44:45]
	v_mov_b64_e32 v[90:91], v[42:43]
	v_mov_b64_e32 v[88:89], v[40:41]
	v_mov_b64_e32 v[86:87], v[38:39]
	v_mov_b64_e32 v[84:85], v[36:37]
	v_mov_b64_e32 v[82:83], v[34:35]
	v_mov_b64_e32 v[80:81], v[32:33]
	v_mov_b64_e32 v[108:109], v[28:29]
	v_mov_b64_e32 v[106:107], v[26:27]
	v_mov_b64_e32 v[104:105], v[24:25]
	v_mov_b64_e32 v[102:103], v[22:23]
	v_mov_b64_e32 v[100:101], v[20:21]
	v_mov_b64_e32 v[98:99], v[18:19]
	v_mov_b64_e32 v[96:97], v[16:17]
	v_mov_b64_e32 v[124:125], v[12:13]
	v_mov_b64_e32 v[122:123], v[10:11]
	v_mov_b64_e32 v[120:121], v[8:9]
	v_mov_b64_e32 v[118:119], v[6:7]
	v_mov_b64_e32 v[116:117], v[4:5]
	v_mov_b64_e32 v[114:115], v[2:3]
	v_mov_b64_e32 v[112:113], v[0:1]
	s_branch .LBB0_562
	s_nop 0
	s_nop 0
	s_nop 0
	s_nop 0
	s_nop 0
	s_nop 0
	s_nop 0
	s_nop 0
	s_nop 0
	s_nop 0
	s_nop 0
	s_nop 0
	s_nop 0
	s_nop 0
	s_nop 0
	s_nop 0
	s_nop 0
	s_nop 0
	s_nop 0
	s_nop 0
	s_nop 0
	s_nop 0
	s_nop 0
	s_nop 0
	s_nop 0
	s_nop 0
